# hand-written hg combine phase: dwordx4 loads, 4 elems per thread, one round trip per iteration
# speedup vs baseline: 1.0166x; 1.0047x over previous
; DI bf16 f2bf(float a) { return (bf16)(pack2(a, 0.f) & 0xffffu); }
; DI int opaque_tid() { int t = threadIdx.x; asm volatile("" : "+v"(t)); return t; }
; DI void peer_hg_phase(const Params& p) {
;   unsigned char* ws = p.ws;
;   const int* ex = (const int*)(ws + OFF_EX);
;   const float* gt = (const float*)(ws + OFF_GT);
;   const float* sd = (const float*)(ws + OFF_SD);
;   const float* pa = (const float*)(ws + OFF_YB);
;   u32* hgp = (u32*)(ws + OFF_HGP);
;   const int tid = opaque_tid();
;   for (size_t i = (size_t)blockIdx.x * 256 + tid; i < (size_t)T_TOK * 128; i += (size_t)gridDim.x * 256) {
;     float a = 0.f;
; #pragma unroll
;     for (int s2 = 0; s2 < 8; ++s2) a += pa[(size_t)s2 * T_TOK * 128 + i];
;     a *= sd[i];
;     const float hgv = 0.5f * a * (1.f + erff(a * 0.70710678118654752f)) * gt[i];
;     hgp[i] = ((u32)ex[i] << 16) | (u32)f2bf(hgv);
;   }
.LBB0_748:
	s_or_b64 exec, exec, s[8:9]
	v_mov_b32_e32 v2, v160
	v_readlane_b32 s0, v255, 7
	s_waitcnt lgkmcnt(0)
	s_barrier
	s_mov_b64 s[10:11], exec
	v_add_u32_e32 v32, s0, v160
	s_lshl_b32 s64, s26, 8
	s_add_u32 s68, s22, 0x10000000
	s_addc_u32 s69, s23, 0
	s_add_u32 s70, s68, 0x800000
	s_addc_u32 s71, s69, 0
	s_add_u32 s72, s70, 0x800000
	s_addc_u32 s73, s71, 0
	s_add_u32 s74, s72, 0x800000
	s_addc_u32 s75, s73, 0
	s_add_u32 s76, s74, 0x800000
	s_addc_u32 s77, s75, 0
	s_add_u32 s78, s76, 0x800000
	s_addc_u32 s79, s77, 0
	s_add_u32 s80, s78, 0x800000
	s_addc_u32 s81, s79, 0
	s_add_u32 s82, s80, 0x800000
	s_addc_u32 s83, s81, 0
	s_add_u32 s84, s22, 0x1c400000
	s_addc_u32 s85, s23, 0
	s_add_u32 s86, s22, 0x18000000
	s_addc_u32 s87, s23, 0
	s_add_u32 s88, s22, 0x17800000
	s_addc_u32 s89, s23, 0
	s_add_u32 s90, s22, 0x1b800000
	s_addc_u32 s91, s23, 0
	s_mov_b32 s92, 0x378e98ab
	s_mov_b32 s93, 0x3b7cd369
	s_mov_b32 s94, 0xbcc618b2
	s_mov_b32 s95, 0x3dda74e4
	s_mov_b32 s96, 0x3f228afd
	s_mov_b32 s97, 0x3e03c728
	s_mov_b32 s98, 0xbfb8aa3b
	s_mov_b32 s99, 0x42ce8ed0
	s_mov_b32 s100, 0xc2b17218
	s_mov_b32 s101, 0x7fffffff
	v_mov_b32_e32 v84, 0x3ba10414
	v_mov_b32_e32 v85, 0xb9c68948
	v_mov_b32_e32 v86, 0x7f800000
	s_mov_b32 s65, 0x80000
.Lmy_hg_loop_L0:
	v_cmp_gt_u32_e32 vcc, s65, v32
	s_and_saveexec_b64 s[66:67], vcc
	s_cbranch_execz .Lmy_hg_done_L0
	v_lshlrev_b32_e32 v33, 4, v32
	global_load_dwordx4 v[36:39], v33, s[68:69]
	global_load_dwordx4 v[40:43], v33, s[70:71]
	global_load_dwordx4 v[44:47], v33, s[72:73]
	global_load_dwordx4 v[48:51], v33, s[74:75]
	global_load_dwordx4 v[52:55], v33, s[76:77]
	global_load_dwordx4 v[56:59], v33, s[78:79]
	global_load_dwordx4 v[60:63], v33, s[80:81]
	global_load_dwordx4 v[64:67], v33, s[82:83]
	global_load_dwordx4 v[68:71], v33, s[84:85]
	global_load_dwordx4 v[72:75], v33, s[86:87]
	global_load_dwordx4 v[76:79], v33, s[88:89]
	s_waitcnt vmcnt(10)
	v_add_f32_e32 v36, 0, v36
	v_add_f32_e32 v37, 0, v37
	v_add_f32_e32 v38, 0, v38
	v_add_f32_e32 v39, 0, v39
	s_waitcnt vmcnt(9)
	v_add_f32_e32 v36, v36, v40
	v_add_f32_e32 v37, v37, v41
	v_add_f32_e32 v38, v38, v42
	v_add_f32_e32 v39, v39, v43
	s_waitcnt vmcnt(8)
	v_add_f32_e32 v36, v36, v44
	v_add_f32_e32 v37, v37, v45
	v_add_f32_e32 v38, v38, v46
	v_add_f32_e32 v39, v39, v47
	s_waitcnt vmcnt(7)
	v_add_f32_e32 v36, v36, v48
	v_add_f32_e32 v37, v37, v49
	v_add_f32_e32 v38, v38, v50
	v_add_f32_e32 v39, v39, v51
	s_waitcnt vmcnt(6)
	v_add_f32_e32 v36, v36, v52
	v_add_f32_e32 v37, v37, v53
	v_add_f32_e32 v38, v38, v54
	v_add_f32_e32 v39, v39, v55
	s_waitcnt vmcnt(5)
	v_add_f32_e32 v36, v36, v56
	v_add_f32_e32 v37, v37, v57
	v_add_f32_e32 v38, v38, v58
	v_add_f32_e32 v39, v39, v59
	s_waitcnt vmcnt(4)
	v_add_f32_e32 v36, v36, v60
	v_add_f32_e32 v37, v37, v61
	v_add_f32_e32 v38, v38, v62
	v_add_f32_e32 v39, v39, v63
	s_waitcnt vmcnt(3)
	v_add_f32_e32 v36, v36, v64
	v_add_f32_e32 v37, v37, v65
	v_add_f32_e32 v38, v38, v66
	v_add_f32_e32 v39, v39, v67
	s_waitcnt vmcnt(2)
	v_mul_f32_e32 v36, v36, v68
	v_mul_f32_e32 v37, v37, v69
	v_mul_f32_e32 v38, v38, v70
	v_mul_f32_e32 v39, v39, v71
	v_mul_f32_e32 v40, 0x3f3504f3, v36
	v_cmp_nlt_f32_e64 s[42:43], |v40|, 1.0
	s_and_saveexec_b64 s[44:45], s[42:43]
	s_xor_b64 s[42:43], exec, s[44:45]
	s_cbranch_execz .Lmy_hg_b_L0_0
	v_fma_f32 v41, |v40|, s92, v85
	v_fma_f32 v41, |v40|, v41, s93
	v_fma_f32 v41, |v40|, v41, s94
	v_fma_f32 v41, |v40|, v41, s95
	v_fma_f32 v41, |v40|, v41, s96
	v_fma_f32 v41, |v40|, v41, s97
	v_fma_f32 v41, |v40|, v41, |v40|
	v_mul_f32_e32 v42, 0xbfb8aa3b, v41
	v_fma_f32 v43, v41, s98, -v42
	v_rndne_f32_e32 v44, v42
	v_fmac_f32_e32 v43, 0xb2a5705f, v41
	v_sub_f32_e32 v42, v42, v44
	v_add_f32_e32 v42, v42, v43
	v_cvt_i32_f32_e32 v43, v44
	v_exp_f32_e32 v42, v42
	v_cmp_nlt_f32_e32 vcc, s99, v41
	v_ldexp_f32 v42, v42, v43
	s_nop 0
	v_cndmask_b32_e32 v42, 0, v42, vcc
	v_cmp_ngt_f32_e32 vcc, s100, v41
	s_nop 1
	v_cndmask_b32_e32 v41, v86, v42, vcc
	v_sub_f32_e32 v41, 1.0, v41
.Lmy_hg_b_L0_0:
	s_andn2_saveexec_b64 s[42:43], s[42:43]
	s_cbranch_execz .Lmy_hg_j_L0_0
	v_mul_f32_e32 v41, v40, v40
	v_fmamk_f32 v42, v41, 0xba1345e1, v84
	v_fmaak_f32 v42, v41, v42, 0xbcdac9b8
	v_fmaak_f32 v42, v41, v42, 0x3de703be
	v_fmaak_f32 v42, v41, v42, 0xbec09330
	v_fmaak_f32 v41, v41, v42, 0x3e0375d0
	v_fma_f32 v41, |v40|, v41, |v40|
.Lmy_hg_j_L0_0:
	s_or_b64 exec, exec, s[42:43]
	v_bfi_b32 v40, s101, v41, v40
	v_mul_f32_e32 v36, 0.5, v36
	v_add_f32_e32 v40, 1.0, v40
	v_mul_f32_e32 v36, v36, v40
	s_waitcnt vmcnt(1)
	v_mul_f32_e32 v36, v72, v36
	v_cvt_pk_bf16_f32 v36, v36, v36
	v_and_b32_e32 v36, 0xffff, v36
	s_waitcnt vmcnt(0)
	v_lshl_or_b32 v80, v76, 16, v36
	v_mul_f32_e32 v40, 0x3f3504f3, v37
	v_cmp_nlt_f32_e64 s[42:43], |v40|, 1.0
	s_and_saveexec_b64 s[44:45], s[42:43]
	s_xor_b64 s[42:43], exec, s[44:45]
	s_cbranch_execz .Lmy_hg_b_L0_1
	v_fma_f32 v41, |v40|, s92, v85
	v_fma_f32 v41, |v40|, v41, s93
	v_fma_f32 v41, |v40|, v41, s94
	v_fma_f32 v41, |v40|, v41, s95
	v_fma_f32 v41, |v40|, v41, s96
	v_fma_f32 v41, |v40|, v41, s97
	v_fma_f32 v41, |v40|, v41, |v40|
	v_mul_f32_e32 v42, 0xbfb8aa3b, v41
	v_fma_f32 v43, v41, s98, -v42
	v_rndne_f32_e32 v44, v42
	v_fmac_f32_e32 v43, 0xb2a5705f, v41
	v_sub_f32_e32 v42, v42, v44
	v_add_f32_e32 v42, v42, v43
	v_cvt_i32_f32_e32 v43, v44
	v_exp_f32_e32 v42, v42
	v_cmp_nlt_f32_e32 vcc, s99, v41
	v_ldexp_f32 v42, v42, v43
	s_nop 0
	v_cndmask_b32_e32 v42, 0, v42, vcc
	v_cmp_ngt_f32_e32 vcc, s100, v41
	s_nop 1
	v_cndmask_b32_e32 v41, v86, v42, vcc
	v_sub_f32_e32 v41, 1.0, v41

; DI bf16 f2bf(float a) { return (bf16)(pack2(a, 0.f) & 0xffffu); }
; DI void peer_hg_phase(const Params& p) {
;     ...
;     a *= sd[i];
;     const float hgv = 0.5f * a * (1.f + erff(a * 0.70710678118654752f)) * gt[i];
;     hgp[i] = ((u32)ex[i] << 16) | (u32)f2bf(hgv);
.Lmy_hg_j_L0_1:
	s_or_b64 exec, exec, s[42:43]
	v_bfi_b32 v40, s101, v41, v40
	v_mul_f32_e32 v37, 0.5, v37
	v_add_f32_e32 v40, 1.0, v40
	v_mul_f32_e32 v37, v37, v40
	v_mul_f32_e32 v37, v73, v37
	v_cvt_pk_bf16_f32 v37, v37, v37
	v_and_b32_e32 v37, 0xffff, v37
	v_lshl_or_b32 v81, v77, 16, v37
	v_mul_f32_e32 v40, 0x3f3504f3, v38
	v_cmp_nlt_f32_e64 s[42:43], |v40|, 1.0
	s_and_saveexec_b64 s[44:45], s[42:43]
	s_xor_b64 s[42:43], exec, s[44:45]
	s_cbranch_execz .Lmy_hg_b_L0_2
	v_fma_f32 v41, |v40|, s92, v85
	v_fma_f32 v41, |v40|, v41, s93
	v_fma_f32 v41, |v40|, v41, s94
	v_fma_f32 v41, |v40|, v41, s95
	v_fma_f32 v41, |v40|, v41, s96
	v_fma_f32 v41, |v40|, v41, s97
	v_fma_f32 v41, |v40|, v41, |v40|
	v_mul_f32_e32 v42, 0xbfb8aa3b, v41
	v_fma_f32 v43, v41, s98, -v42
	v_rndne_f32_e32 v44, v42
	v_fmac_f32_e32 v43, 0xb2a5705f, v41
	v_sub_f32_e32 v42, v42, v44
	v_add_f32_e32 v42, v42, v43
	v_cvt_i32_f32_e32 v43, v44
	v_exp_f32_e32 v42, v42
	v_cmp_nlt_f32_e32 vcc, s99, v41
	v_ldexp_f32 v42, v42, v43
	s_nop 0
	v_cndmask_b32_e32 v42, 0, v42, vcc
	v_cmp_ngt_f32_e32 vcc, s100, v41
	s_nop 1
	v_cndmask_b32_e32 v41, v86, v42, vcc
	v_sub_f32_e32 v41, 1.0, v41

; DI bf16 f2bf(float a) { return (bf16)(pack2(a, 0.f) & 0xffffu); }
; DI void peer_hg_phase(const Params& p) {
;     ...
;     a *= sd[i];
;     const float hgv = 0.5f * a * (1.f + erff(a * 0.70710678118654752f)) * gt[i];
;     hgp[i] = ((u32)ex[i] << 16) | (u32)f2bf(hgv);
.Lmy_hg_j_L0_2:
	s_or_b64 exec, exec, s[42:43]
	v_bfi_b32 v40, s101, v41, v40
	v_mul_f32_e32 v38, 0.5, v38
	v_add_f32_e32 v40, 1.0, v40
	v_mul_f32_e32 v38, v38, v40
	v_mul_f32_e32 v38, v74, v38
	v_cvt_pk_bf16_f32 v38, v38, v38
	v_and_b32_e32 v38, 0xffff, v38
	v_lshl_or_b32 v82, v78, 16, v38
	v_mul_f32_e32 v40, 0x3f3504f3, v39
	v_cmp_nlt_f32_e64 s[42:43], |v40|, 1.0
	s_and_saveexec_b64 s[44:45], s[42:43]
	s_xor_b64 s[42:43], exec, s[44:45]
	s_cbranch_execz .Lmy_hg_b_L0_3
	v_fma_f32 v41, |v40|, s92, v85
	v_fma_f32 v41, |v40|, v41, s93
	v_fma_f32 v41, |v40|, v41, s94
	v_fma_f32 v41, |v40|, v41, s95
	v_fma_f32 v41, |v40|, v41, s96
	v_fma_f32 v41, |v40|, v41, s97
	v_fma_f32 v41, |v40|, v41, |v40|
	v_mul_f32_e32 v42, 0xbfb8aa3b, v41
	v_fma_f32 v43, v41, s98, -v42
	v_rndne_f32_e32 v44, v42
	v_fmac_f32_e32 v43, 0xb2a5705f, v41
	v_sub_f32_e32 v42, v42, v44
	v_add_f32_e32 v42, v42, v43
	v_cvt_i32_f32_e32 v43, v44
	v_exp_f32_e32 v42, v42
	v_cmp_nlt_f32_e32 vcc, s99, v41
	v_ldexp_f32 v42, v42, v43
	s_nop 0
	v_cndmask_b32_e32 v42, 0, v42, vcc
	v_cmp_ngt_f32_e32 vcc, s100, v41
	s_nop 1
	v_cndmask_b32_e32 v41, v86, v42, vcc
	v_sub_f32_e32 v41, 1.0, v41

; DI bf16 f2bf(float a) { return (bf16)(pack2(a, 0.f) & 0xffffu); }
; DI void peer_hg_phase(const Params& p) {
;     ...
;     a *= sd[i];
;     const float hgv = 0.5f * a * (1.f + erff(a * 0.70710678118654752f)) * gt[i];
;     hgp[i] = ((u32)ex[i] << 16) | (u32)f2bf(hgv);
;   }
.Lmy_hg_j_L0_3:
	s_or_b64 exec, exec, s[42:43]
	v_bfi_b32 v40, s101, v41, v40
	v_mul_f32_e32 v39, 0.5, v39
	v_add_f32_e32 v40, 1.0, v40
	v_mul_f32_e32 v39, v39, v40
	v_mul_f32_e32 v39, v75, v39
	v_cvt_pk_bf16_f32 v39, v39, v39
	v_and_b32_e32 v39, 0xffff, v39
	v_lshl_or_b32 v83, v79, 16, v39
	global_store_dwordx4 v33, v[80:83], s[90:91]
	v_add_u32_e32 v32, s64, v32
	s_or_b64 exec, exec, s[66:67]
	s_branch .Lmy_hg_loop_L0
.Lmy_hg_done_L0:
	s_or_b64 exec, exec, s[66:67]

; DI int opaque_tid() { int t = threadIdx.x; asm volatile("" : "+v"(t)); return t; }
; DI void peer_hg_phase(const Params& p) {
;   unsigned char* ws = p.ws;
;   const int* ex = (const int*)(ws + OFF_EX);
;   const float* gt = (const float*)(ws + OFF_GT);
;   const float* sd = (const float*)(ws + OFF_SD);
;   const float* pa = (const float*)(ws + OFF_YB);
;   u32* hgp = (u32*)(ws + OFF_HGP);
;   const int tid = opaque_tid();
;   for (size_t i = (size_t)blockIdx.x * 256 + tid; i < (size_t)T_TOK * 128; i += (size_t)gridDim.x * 256) {
;     float a = 0.f;
; #pragma unroll
;     for (int s2 = 0; s2 < 8; ++s2) a += pa[(size_t)s2 * T_TOK * 128 + i];
.LBB0_1571:
	s_or_b64 exec, exec, s[6:7]
	v_mov_b32_e32 v2, v160
	v_readlane_b32 s0, v255, 7
	s_waitcnt lgkmcnt(0)
	s_barrier
	s_mov_b64 s[6:7], exec
	v_add_u32_e32 v32, s0, v160
	s_lshl_b32 s64, s26, 8
	s_add_u32 s68, s22, 0x10000000
	s_addc_u32 s69, s23, 0
	s_add_u32 s70, s68, 0x800000
	s_addc_u32 s71, s69, 0
	s_add_u32 s72, s70, 0x800000
	s_addc_u32 s73, s71, 0
	s_add_u32 s74, s72, 0x800000
	s_addc_u32 s75, s73, 0
	s_add_u32 s76, s74, 0x800000
	s_addc_u32 s77, s75, 0
	s_add_u32 s78, s76, 0x800000
	s_addc_u32 s79, s77, 0
	s_add_u32 s80, s78, 0x800000
	s_addc_u32 s81, s79, 0
	s_add_u32 s82, s80, 0x800000
	s_addc_u32 s83, s81, 0
	s_add_u32 s84, s22, 0x1c400000
	s_addc_u32 s85, s23, 0
	s_add_u32 s86, s22, 0x18000000
	s_addc_u32 s87, s23, 0
	s_add_u32 s88, s22, 0x17800000
	s_addc_u32 s89, s23, 0
	s_add_u32 s90, s22, 0x1b800000
	s_addc_u32 s91, s23, 0
	s_mov_b32 s92, 0x378e98ab
	s_mov_b32 s93, 0x3b7cd369
	s_mov_b32 s94, 0xbcc618b2
	s_mov_b32 s95, 0x3dda74e4
	s_mov_b32 s96, 0x3f228afd
	s_mov_b32 s97, 0x3e03c728
	s_mov_b32 s98, 0xbfb8aa3b
	s_mov_b32 s99, 0x42ce8ed0
	s_mov_b32 s100, 0xc2b17218
	s_mov_b32 s101, 0x7fffffff
	v_mov_b32_e32 v84, 0x3ba10414
	v_mov_b32_e32 v85, 0xb9c68948
	v_mov_b32_e32 v86, 0x7f800000
	s_mov_b32 s65, 0x80000
